# fast loop without wave priority (both halves of the workgroup at priority 0)
# baseline (speedup 1.0000x reference)
; #define LAS __attribute__((address_space(3)))
; __device__ __forceinline__ int v_st_nat(int k, int c) { return ((k >> 3) * 2 + (c >> 5)) * 512 + ((k & 7) * 32 + (c & 31)) * 2; }
; __device__ __forceinline__ int v_rd_base(int lane) { return ((lane & 3) << 3) | (((lane >> 2) & 3) << 6) | (((lane >> 4) & 1) << 5) | (((lane >> 5) & 1) << 8); }
; #define AT_LOAD(K0, K1, V0, V1, T) do { const size_t e_ = (size_t)(128 * (T) + sr) * 64 + sc; \
;         K0 = *(const bf16x8*)(kcp + e_); V0 = *(const bf16x8*)(vcp + e_); K1 = *(const bf16x8*)(kcp + e_ + 64 * 64); V1 = *(const bf16x8*)(vcp + e_ + 64 * 64); } while (0)
; #define AT_STORE(K0, K1, V0, V1, BUF) do { *(LAS bf16x8*)(lds + AT_K + (BUF) * AT_KB + kst0) = K0; *(LAS bf16x8*)(lds + AT_K + (BUF) * AT_KB + kst1) = K1; \
;         *(LAS bf16x8*)(lds + AT_V + (BUF) * AT_VB + vst0) = V0; *(LAS bf16x8*)(lds + AT_V + (BUF) * AT_VB + vst1) = V1; } while (0)
; template <int VAR>
; __device__ __forceinline__ void attn_unit(const Args& a, int l, int b, int h, int qrow0  , bool ctxu, const bf16* Z, bf16* Y, LAS unsigned char* lds) {
;     ...
;     const int sr = tid >> 3, sc = (tid & 7) * 8;
;     const int kst0 = sr * 144 + sc * 2, kst1 = kst0 + 64 * 144, vst0 = v_st_nat(sr, sc), vst1 = v_st_nat(sr + 64, sc);
;     const int vb0 = (int)(unsigned)(uintptr_t)(lds + AT_V) + v_rd_base(lane);
;     LAS float* wsf = (LAS float*)(lds + AT_WS) + wave * 64;
;     f32x16 negm = f32x16{}, o0 = f32x16{}, o1 = f32x16{}, lacc = f32x16{};
;     float m = 0.f;
;     bf16x8 ka0, ka1, va0, va1, kb0, kb1, vb0_, vb1_;
;     ...
;     AT_LOAD(ka0, ka1, va0, va1, 0); AT_LOAD(kb0, kb1, vb0_, vb1_, 1); AT_STORE(ka0, ka1, va0, va1, 0);
;     const LAS unsigned char* Kb0 = lds + AT_K + comp * 64;
;     for (int t = 0; t < NT; t += 2) {
;         __syncthreads();
;         if (t + 2 < NT) AT_LOAD(ka0, ka1, va0, va1, t + 2);
.LBB0_431:
	v_mov_b32_e32 v79, 0
	v_readfirstlane_b32 s36, v230
	v_readfirstlane_b32 s37, v231
	s_mov_b32 s94, 1
	s_mov_b32 s95, 1
	s_mov_b32 s33, 0
	s_lshr_b32 s50, s29, 6
	s_lshl_b32 s51, s50, 10
	s_lshl_b32 s93, s50, 8
	s_lshl_b32 s50, s50, 3
	v_lshrrev_b32_e32 v132, 3, v227
	v_add_u32_e32 v132, s50, v132
	v_bfe_u32 v133, v132, 1, 3
	v_and_b32_e32 v134, 7, v227
	v_xor_b32_e32 v134, v134, v133
	v_lshlrev_b32_e32 v132, 7, v132
	v_lshl_or_b32 v158, v134, 4, v132
	v_add_u32_e32 v159, 0x2000, v158
	v_bfe_u32 v132, v227, 2, 3
	v_add_u32_e32 v132, s50, v132
	v_lshrrev_b32_e32 v133, 5, v227
	v_and_b32_e32 v134, 3, v227
	v_lshlrev_b32_e32 v133, 6, v133
	v_lshl_or_b32 v133, v134, 4, v133
	v_lshl_or_b32 v160, v132, 7, v133
	v_add_u32_e32 v161, 0x2000, v160
	s_lshl_b32 s50, s8, 2
	v_add_u32_e32 v132, s50, v248
	v_bfe_u32 v133, v247, 1, 3
	v_xor_b32_e32 v132, v132, v133
	v_lshlrev_b32_e32 v133, 7, v247
	v_lshl_or_b32 v144, v132, 4, v133
	v_xor_b32_e32 v145, 32, v144
	v_add_u32_e32 v146, 0x3000, v249
	s_add_u32 s93, s93, 0x19800
	v_lshlrev_b32_e32 v132, 2, v247
	v_add_u32_e32 v148, s93, v132
	v_lshlrev_b32_e32 v132, 4, v248
	v_add_u32_e32 v147, s93, v132
	v_mov_b32_e32 v132, 0x19880
	v_mov_b32_e32 v133, 0
	ds_write_b32 v132, v133
	v_mov_b32_e32 v80, 0
	v_mov_b32_e32 v200, 0
	v_mov_b32_e32 v81, 0
	v_mov_b32_e32 v201, 0
	v_mov_b32_e32 v82, 0
	v_mov_b32_e32 v202, 0
	v_mov_b32_e32 v83, 0
	v_mov_b32_e32 v203, 0
	v_mov_b32_e32 v84, 0
	v_mov_b32_e32 v204, 0
	v_mov_b32_e32 v85, 0
	v_mov_b32_e32 v205, 0
	v_mov_b32_e32 v86, 0
	v_mov_b32_e32 v206, 0
	v_mov_b32_e32 v87, 0
	v_mov_b32_e32 v207, 0
	v_mov_b32_e32 v88, 0
	v_mov_b32_e32 v208, 0
	v_mov_b32_e32 v89, 0
	v_mov_b32_e32 v209, 0
	v_mov_b32_e32 v90, 0
	v_mov_b32_e32 v210, 0
	v_mov_b32_e32 v91, 0
	v_mov_b32_e32 v211, 0
	v_mov_b32_e32 v92, 0
	v_mov_b32_e32 v212, 0
	v_mov_b32_e32 v93, 0
	v_mov_b32_e32 v213, 0
	v_mov_b32_e32 v94, 0
	v_mov_b32_e32 v214, 0
	v_mov_b32_e32 v95, 0
	v_mov_b32_e32 v215, 0
	v_mov_b32_e32 v128, 0
	v_mov_b32_e32 v129, 0
	v_mov_b32_e32 v130, 0
	v_mov_b32_e32 v131, 0
	v_mov_b32_e32 v149, 0
	s_sub_u32 s36, s36, s51
	s_subb_u32 s37, s37, 0
	s_add_u32 s48, s36, 0x1d200000
	s_addc_u32 s49, s37, 0
	s_add_u32 s36, s36, 0x1c000000
	s_addc_u32 s37, s37, 0
	s_waitcnt lgkmcnt(0)
	s_add_u32 m0, s51, 0x0
	s_nop 0
	global_load_lds_dwordx4 v158, s[36:37]
	s_add_u32 m0, s51, 0x2000
	s_nop 0
	global_load_lds_dwordx4 v159, s[36:37]
	s_add_u32 m0, s51, 0xc000
	s_nop 0
	global_load_lds_dwordx4 v160, s[48:49]
	s_add_u32 m0, s51, 0xe000
	s_nop 0
	global_load_lds_dwordx4 v161, s[48:49]
	s_add_u32 s36, s36, 0x4000
	s_addc_u32 s37, s37, 0
	s_add_u32 s48, s48, 0x4000
	s_addc_u32 s49, s49, 0
	s_add_u32 m0, s51, 0x4000
	s_nop 0
	global_load_lds_dwordx4 v158, s[36:37]
	s_add_u32 m0, s51, 0x6000
	s_nop 0
	global_load_lds_dwordx4 v159, s[36:37]
	s_add_u32 m0, s51, 0x10000
	s_nop 0
	global_load_lds_dwordx4 v160, s[48:49]
	s_add_u32 m0, s51, 0x12000
	s_nop 0
	global_load_lds_dwordx4 v161, s[48:49]
	s_add_u32 s36, s36, 0x4000
	s_addc_u32 s37, s37, 0
	s_add_u32 s48, s48, 0x4000
	s_addc_u32 s49, s49, 0
	s_waitcnt vmcnt(4)
	s_barrier
	s_add_u32 m0, s51, 0x8000
	s_nop 0
	global_load_lds_dwordx4 v158, s[36:37]
	s_add_u32 m0, s51, 0xa000
	s_nop 0
	global_load_lds_dwordx4 v159, s[36:37]
	s_add_u32 m0, s51, 0x14000
	s_nop 0
	global_load_lds_dwordx4 v160, s[48:49]
	s_add_u32 m0, s51, 0x16000
	s_nop 0
	global_load_lds_dwordx4 v161, s[48:49]
	s_add_u32 s36, s36, 0x4000
	s_addc_u32 s37, s37, 0
	s_add_u32 s48, s48, 0x4000
	s_addc_u32 s49, s49, 0
	ds_read_b128 v[48:51], v144 offset:0
	ds_read_b128 v[52:55], v145 offset:0
	ds_read_b128 v[56:59], v144 offset:4096
	ds_read_b128 v[60:63], v145 offset:4096

; #define LAS __attribute__((address_space(3)))
; __device__ __forceinline__ int crow(int r, int hi) { return (r & 3) + 8 * (r >> 2) + 4 * hi; }
; #define AT_LOAD(K0, K1, V0, V1, T) do { const size_t e_ = (size_t)(128 * (T) + sr) * 64 + sc; \
;         K0 = *(const bf16x8*)(kcp + e_); V0 = *(const bf16x8*)(vcp + e_); K1 = *(const bf16x8*)(kcp + e_ + 64 * 64); V1 = *(const bf16x8*)(vcp + e_ + 64 * 64); } while (0)
; #define AT_STORE(K0, K1, V0, V1, BUF) do { *(LAS bf16x8*)(lds + AT_K + (BUF) * AT_KB + kst0) = K0; *(LAS bf16x8*)(lds + AT_K + (BUF) * AT_KB + kst1) = K1; \
;         *(LAS bf16x8*)(lds + AT_V + (BUF) * AT_VB + vst0) = V0; *(LAS bf16x8*)(lds + AT_V + (BUF) * AT_VB + vst1) = V1; } while (0)
; template <int VAR>
; __device__ __forceinline__ void attn_unit(const Args& a, int l, int b, int h, int qrow0  , bool ctxu, const bf16* Z, bf16* Y, LAS unsigned char* lds) {
;     ...
;     for (int t = 0; t < NT; t += 2) {
;         __syncthreads();
;         if (t + 2 < NT) AT_LOAD(ka0, ka1, va0, va1, t + 2);
;         attn_tile(Kb0, vb0, q0, q1, negm, m, o0, o1, lacc, t == 0, wsf, r32, hi);
;         AT_STORE(kb0, kb1, vb0_, vb1_, 1);
;         __syncthreads();
;         if (t + 3 < NT) AT_LOAD(kb0, kb1, vb0_, vb1_, t + 3);
;         attn_tile(Kb0 + AT_KB, vb0 + AT_VB, q0, q1, negm, m, o0, o1, lacc, false, wsf, r32, hi);
;         if (t + 2 < NT) AT_STORE(ka0, ka1, va0, va1, 0);
;     }
;     ...
;     float lam, omli;
;     { float s1 = 0.f, s2 = 0.f;
;       for (int i = 0; i < 32; ++i) { s1 += a.lam_q1[l * 32 + i] * a.lam_k1[l * 32 + i]; s2 += a.lam_q2[l * 32 + i] * a.lam_k2[l * 32 + i]; }
;       const float li = 0.8f - 0.6f * expf(-0.3f * (float)l); lam = expf(s1) - expf(s2) + li; omli = 1.f - li; }
;     LAS float* stg = (LAS float*)(lds + AT_ST) + wq * 2048;
;     if (comp == 1) {
; #pragma unroll
;         for (int r = 0; r < 16; ++r) { const int qr = crow(r, hi); const float il = lam * __builtin_amdgcn_rcpf(lacc[r]); stg[qr * 64 + r32] = o0[r] * il; stg[qr * 64 + 32 + r32] = o1[r] * il; }
;     }
;     __syncthreads();
;     if (comp == 0) {
; #pragma unroll
;         for (int r = 0; r < 16; ++r) { const int qr = crow(r, hi); const float il = __builtin_amdgcn_rcpf(lacc[r]); o0[r] = o0[r] * il - stg[qr * 64 + r32]; o1[r] = o1[r] * il - stg[qr * 64 + 32 + r32]; }
.Lat_ndF5:
	ds_read_b128 v[48:51], v144 offset:0
	ds_read_b128 v[52:55], v145 offset:0
	ds_read_b128 v[56:59], v144 offset:4096
	ds_read_b128 v[60:63], v145 offset:4096
	v_mfma_f32_32x32x16_bf16 v[80:95], v[162:165], v[192:195], v[80:95]
	v_mfma_f32_32x32x16_bf16 v[200:215], v[162:165], v[196:199], v[200:215]
	s_add_u32 s33, s33, 1
	s_cmp_lt_u32 s33, 22
	s_cbranch_scc1 .Lat_floop
	v_add_f32_e32 v132, v128, v129
	v_mov_b32_e32 v133, v132
	s_nop 1
	v_permlane32_swap_b32_e32 v132, v133
	v_add_f32_e32 v135, v132, v133
	v_add_f32_e32 v132, v130, v131
	v_mov_b32_e32 v133, v132
	s_nop 1
	v_permlane32_swap_b32_e32 v132, v133
	v_add_f32_e32 v130, v132, v133
	s_nop 7
	s_nop 7
	v_add_f32_e32 v132, v135, v130
	v_mov_b32_e32 v133, 0
	v_add_f32_e64 v132, v132, |v0|
	v_add_f32_e64 v133, v133, |v1|
	v_add_f32_e64 v132, v132, |v2|
	v_add_f32_e64 v133, v133, |v3|
	v_add_f32_e64 v132, v132, |v4|
	v_add_f32_e64 v133, v133, |v5|
	v_add_f32_e64 v132, v132, |v6|
	v_add_f32_e64 v133, v133, |v7|
	v_add_f32_e64 v132, v132, |v8|
	v_add_f32_e64 v133, v133, |v9|
	v_add_f32_e64 v132, v132, |v10|
	v_add_f32_e64 v133, v133, |v11|
	v_add_f32_e64 v132, v132, |v12|
	v_add_f32_e64 v133, v133, |v13|
	v_add_f32_e64 v132, v132, |v14|
	v_add_f32_e64 v133, v133, |v15|
	v_add_f32_e64 v132, v132, |v16|
	v_add_f32_e64 v133, v133, |v17|
	v_add_f32_e64 v132, v132, |v18|
	v_add_f32_e64 v133, v133, |v19|
	v_add_f32_e64 v132, v132, |v20|
	v_add_f32_e64 v133, v133, |v21|
	v_add_f32_e64 v132, v132, |v22|
	v_add_f32_e64 v133, v133, |v23|
	v_add_f32_e64 v132, v132, |v24|
	v_add_f32_e64 v133, v133, |v25|
	v_add_f32_e64 v132, v132, |v26|
	v_add_f32_e64 v133, v133, |v27|
	v_add_f32_e64 v132, v132, |v28|
	v_add_f32_e64 v133, v133, |v29|
	v_add_f32_e64 v132, v132, |v30|
	v_add_f32_e64 v133, v133, |v31|
	v_add_f32_e64 v132, v132, |v80|
	v_add_f32_e64 v133, v133, |v81|
	v_add_f32_e64 v132, v132, |v82|
	v_add_f32_e64 v133, v133, |v83|
	v_add_f32_e64 v132, v132, |v84|
	v_add_f32_e64 v133, v133, |v85|
	v_add_f32_e64 v132, v132, |v86|
	v_add_f32_e64 v133, v133, |v87|
	v_add_f32_e64 v132, v132, |v88|
	v_add_f32_e64 v133, v133, |v89|
	v_add_f32_e64 v132, v132, |v90|
	v_add_f32_e64 v133, v133, |v91|
	v_add_f32_e64 v132, v132, |v92|
	v_add_f32_e64 v133, v133, |v93|
	v_add_f32_e64 v132, v132, |v94|
	v_add_f32_e64 v133, v133, |v95|
	v_add_f32_e64 v132, v132, |v200|
	v_add_f32_e64 v133, v133, |v201|
	v_add_f32_e64 v132, v132, |v202|
	v_add_f32_e64 v133, v133, |v203|
	v_add_f32_e64 v132, v132, |v204|
	v_add_f32_e64 v133, v133, |v205|
	v_add_f32_e64 v132, v132, |v206|
	v_add_f32_e64 v133, v133, |v207|
	v_add_f32_e64 v132, v132, |v208|
	v_add_f32_e64 v133, v133, |v209|
	v_add_f32_e64 v132, v132, |v210|
	v_add_f32_e64 v133, v133, |v211|
	v_add_f32_e64 v132, v132, |v212|
	v_add_f32_e64 v133, v133, |v213|
	v_add_f32_e64 v132, v132, |v214|
	v_add_f32_e64 v133, v133, |v215|
	v_add_f32_e32 v132, v132, v133
	v_mov_b32_e32 v133, 0x76800000
	v_cmp_nlt_f32_e32 vcc, v132, v133
	s_cmp_lg_u64 vcc, 0
	s_cselect_b32 s50, 1, 0
	v_mov_b32_e32 v134, 0x19880
	v_mov_b32_e32 v133, s50
	ds_or_b32 v134, v133
	s_waitcnt lgkmcnt(0)
	s_barrier
	ds_read_b32 v133, v134
	s_waitcnt lgkmcnt(0)
	v_readfirstlane_b32 s50, v133
	s_cmp_lg_u32 s50, 0
	s_cbranch_scc1 .Lat_safe_entry
	s_nop 7
	s_waitcnt lgkmcnt(0)
	ds_write_b32 v148, v135
	s_waitcnt lgkmcnt(0)
	ds_read_b128 v[32:35], v147 offset:0
	ds_read_b128 v[36:39], v147 offset:32
	ds_read_b128 v[40:43], v147 offset:64
	ds_read_b128 v[44:47], v147 offset:96
	s_waitcnt lgkmcnt(0)
	s_mov_b32 s93, 0
	s_waitcnt vmcnt(0)
	v_or_b32_e32 v132, s58, v228
	v_mov_b32_e32 v133, 0
	v_lshl_add_u64 v[132:133], v[132:133], 2, s[78:79]
	global_load_dwordx4 v[100:103], v[132:133], off offset:16
	global_load_dwordx4 v[96:99], v[132:133], off
	s_branch .LBB0_459

; #define LAS __attribute__((address_space(3)))
; __device__ __forceinline__ int v_st_nat(int k, int c) { return ((k >> 3) * 2 + (c >> 5)) * 512 + ((k & 7) * 32 + (c & 31)) * 2; }
; __device__ __forceinline__ int v_rd_base(int lane) { return ((lane & 3) << 3) | (((lane >> 2) & 3) << 6) | (((lane >> 4) & 1) << 5) | (((lane >> 5) & 1) << 8); }
; #define AT_LOAD(K0, K1, V0, V1, T) do { const size_t e_ = (size_t)(128 * (T) + sr) * 64 + sc; \
;         K0 = *(const bf16x8*)(kcp + e_); V0 = *(const bf16x8*)(vcp + e_); K1 = *(const bf16x8*)(kcp + e_ + 64 * 64); V1 = *(const bf16x8*)(vcp + e_ + 64 * 64); } while (0)
; #define AT_STORE(K0, K1, V0, V1, BUF) do { *(LAS bf16x8*)(lds + AT_K + (BUF) * AT_KB + kst0) = K0; *(LAS bf16x8*)(lds + AT_K + (BUF) * AT_KB + kst1) = K1; \
;         *(LAS bf16x8*)(lds + AT_V + (BUF) * AT_VB + vst0) = V0; *(LAS bf16x8*)(lds + AT_V + (BUF) * AT_VB + vst1) = V1; } while (0)
; template <int VAR>
; __device__ __forceinline__ void attn_unit(const Args& a, int l, int b, int h, int qrow0  , bool ctxu, const bf16* Z, bf16* Y, LAS unsigned char* lds) {
;     ...
;     const int sr = tid >> 3, sc = (tid & 7) * 8;
;     const int kst0 = sr * 144 + sc * 2, kst1 = kst0 + 64 * 144, vst0 = v_st_nat(sr, sc), vst1 = v_st_nat(sr + 64, sc);
;     const int vb0 = (int)(unsigned)(uintptr_t)(lds + AT_V) + v_rd_base(lane);
;     LAS float* wsf = (LAS float*)(lds + AT_WS) + wave * 64;
;     f32x16 negm = f32x16{}, o0 = f32x16{}, o1 = f32x16{}, lacc = f32x16{};
;     float m = 0.f;
;     bf16x8 ka0, ka1, va0, va1, kb0, kb1, vb0_, vb1_;
;     ...
;     AT_LOAD(ka0, ka1, va0, va1, 0); AT_LOAD(kb0, kb1, vb0_, vb1_, 1); AT_STORE(ka0, ka1, va0, va1, 0);
;     const LAS unsigned char* Kb0 = lds + AT_K + comp * 64;
;     for (int t = 0; t < NT; t += 2) {
;         __syncthreads();
;         if (t + 2 < NT) AT_LOAD(ka0, ka1, va0, va1, t + 2);
.Lat_safe_entry:
	s_barrier
	v_mov_b32_e32 v0, 0
	v_mov_b32_e32 v1, 0
	v_mov_b32_e32 v2, 0
	v_mov_b32_e32 v3, 0
	v_mov_b32_e32 v4, 0
	v_mov_b32_e32 v5, 0
	v_mov_b32_e32 v6, 0
	v_mov_b32_e32 v7, 0
	v_mov_b32_e32 v8, 0
	v_mov_b32_e32 v9, 0
	v_mov_b32_e32 v10, 0
	v_mov_b32_e32 v11, 0
	v_mov_b32_e32 v12, 0
	v_mov_b32_e32 v13, 0
	v_mov_b32_e32 v14, 0
	v_mov_b32_e32 v15, 0
	v_mov_b32_e32 v16, 0
	v_mov_b32_e32 v17, 0
	v_mov_b32_e32 v18, 0
	v_mov_b32_e32 v19, 0
	v_mov_b32_e32 v20, 0
	v_mov_b32_e32 v21, 0
	v_mov_b32_e32 v22, 0
	v_mov_b32_e32 v23, 0
	v_mov_b32_e32 v24, 0
	v_mov_b32_e32 v25, 0
	v_mov_b32_e32 v26, 0
	v_mov_b32_e32 v27, 0
	v_mov_b32_e32 v28, 0
	v_mov_b32_e32 v29, 0
	v_mov_b32_e32 v30, 0
	v_mov_b32_e32 v31, 0
	v_mov_b32_e32 v32, 0
	v_mov_b32_e32 v33, 0
	v_mov_b32_e32 v34, 0
	v_mov_b32_e32 v35, 0
	v_mov_b32_e32 v36, 0
	v_mov_b32_e32 v37, 0
	v_mov_b32_e32 v38, 0
	v_mov_b32_e32 v39, 0
	v_mov_b32_e32 v40, 0
	v_mov_b32_e32 v41, 0
	v_mov_b32_e32 v42, 0
	v_mov_b32_e32 v43, 0
	v_mov_b32_e32 v44, 0
	v_mov_b32_e32 v45, 0
	v_mov_b32_e32 v46, 0
	v_mov_b32_e32 v47, 0
	v_mov_b32_e32 v64, 0
	v_mov_b32_e32 v65, 0
	v_mov_b32_e32 v66, 0
	v_mov_b32_e32 v67, 0
	v_mov_b32_e32 v68, 0
	v_mov_b32_e32 v69, 0
	v_mov_b32_e32 v70, 0
	v_mov_b32_e32 v71, 0
	v_mov_b32_e32 v72, 0
	v_mov_b32_e32 v73, 0
	v_mov_b32_e32 v74, 0
	v_mov_b32_e32 v75, 0
	v_mov_b32_e32 v76, 0
	v_mov_b32_e32 v77, 0
	v_mov_b32_e32 v78, 0
	v_mov_b32_e32 v79, 0
	v_mov_b32_e32 v234, 0
	v_mov_b32_e32 v79, 0
	v_readfirstlane_b32 s36, v230
	v_readfirstlane_b32 s37, v231
	s_mov_b32 s94, 1
	s_mov_b32 s95, 1
	s_mov_b32 s33, 0
	s_lshr_b32 s50, s29, 6
	s_lshl_b32 s51, s50, 10
	s_lshl_b32 s93, s50, 8
	s_lshl_b32 s50, s50, 3
	v_lshrrev_b32_e32 v132, 3, v227
	v_add_u32_e32 v132, s50, v132
	v_bfe_u32 v133, v132, 1, 3
	v_and_b32_e32 v134, 7, v227
	v_xor_b32_e32 v134, v134, v133
	v_lshlrev_b32_e32 v132, 7, v132
	v_lshl_or_b32 v158, v134, 4, v132
	v_add_u32_e32 v159, 0x2000, v158
	v_bfe_u32 v132, v227, 2, 3
	v_add_u32_e32 v132, s50, v132
	v_lshrrev_b32_e32 v133, 5, v227
	v_and_b32_e32 v134, 3, v227
	v_lshlrev_b32_e32 v133, 6, v133
	v_lshl_or_b32 v133, v134, 4, v133
	v_lshl_or_b32 v160, v132, 7, v133
	v_add_u32_e32 v161, 0x2000, v160
	s_lshl_b32 s50, s8, 2
	v_add_u32_e32 v132, s50, v248
	v_bfe_u32 v133, v247, 1, 3
	v_xor_b32_e32 v132, v132, v133
	v_lshlrev_b32_e32 v133, 7, v247
	v_lshl_or_b32 v144, v132, 4, v133
	v_xor_b32_e32 v145, 32, v144
	v_add_u32_e32 v146, 0x3000, v249
	s_add_u32 s93, s93, 0x19800
	v_lshlrev_b32_e32 v132, 2, v247
	v_add_u32_e32 v148, s93, v132
	v_lshlrev_b32_e32 v132, 4, v248
	v_add_u32_e32 v147, s93, v132
	v_mov_b32_e32 v132, 0x19880
	v_mov_b32_e32 v133, 0
	ds_write_b32 v132, v133
	v_mov_b32_e32 v80, 0
	v_mov_b32_e32 v200, 0
	v_mov_b32_e32 v81, 0
	v_mov_b32_e32 v201, 0
	v_mov_b32_e32 v82, 0
	v_mov_b32_e32 v202, 0
	v_mov_b32_e32 v83, 0
	v_mov_b32_e32 v203, 0
	v_mov_b32_e32 v84, 0
	v_mov_b32_e32 v204, 0
	v_mov_b32_e32 v85, 0
	v_mov_b32_e32 v205, 0
	v_mov_b32_e32 v86, 0
	v_mov_b32_e32 v206, 0
	v_mov_b32_e32 v87, 0
	v_mov_b32_e32 v207, 0
	v_mov_b32_e32 v88, 0
	v_mov_b32_e32 v208, 0
	v_mov_b32_e32 v89, 0
	v_mov_b32_e32 v209, 0
	v_mov_b32_e32 v90, 0
	v_mov_b32_e32 v210, 0
	v_mov_b32_e32 v91, 0
	v_mov_b32_e32 v211, 0
	v_mov_b32_e32 v92, 0
	v_mov_b32_e32 v212, 0
	v_mov_b32_e32 v93, 0
	v_mov_b32_e32 v213, 0
	v_mov_b32_e32 v94, 0
	v_mov_b32_e32 v214, 0
	v_mov_b32_e32 v95, 0
	v_mov_b32_e32 v215, 0
	v_mov_b32_e32 v128, 0
	v_mov_b32_e32 v129, 0
	v_mov_b32_e32 v130, 0
	v_mov_b32_e32 v131, 0
	v_mov_b32_e32 v149, 0
	s_sub_u32 s36, s36, s51
	s_subb_u32 s37, s37, 0
	s_add_u32 s48, s36, 0x1d200000
	s_addc_u32 s49, s37, 0
	s_add_u32 s36, s36, 0x1c000000
	s_addc_u32 s37, s37, 0
	s_waitcnt lgkmcnt(0)
	s_add_u32 m0, s51, 0x0
	s_nop 0
	global_load_lds_dwordx4 v158, s[36:37]
	s_add_u32 m0, s51, 0x2000
	s_nop 0
	global_load_lds_dwordx4 v159, s[36:37]
	s_add_u32 m0, s51, 0xc000
	s_nop 0
	global_load_lds_dwordx4 v160, s[48:49]
	s_add_u32 m0, s51, 0xe000
	s_nop 0
	global_load_lds_dwordx4 v161, s[48:49]
	s_add_u32 s36, s36, 0x4000
	s_addc_u32 s37, s37, 0
	s_add_u32 s48, s48, 0x4000
	s_addc_u32 s49, s49, 0
	s_add_u32 m0, s51, 0x4000
	s_nop 0
	global_load_lds_dwordx4 v158, s[36:37]
	s_add_u32 m0, s51, 0x6000
	s_nop 0
	global_load_lds_dwordx4 v159, s[36:37]
	s_add_u32 m0, s51, 0x10000
	s_nop 0
	global_load_lds_dwordx4 v160, s[48:49]
	s_add_u32 m0, s51, 0x12000
	s_nop 0
	global_load_lds_dwordx4 v161, s[48:49]
	s_add_u32 s36, s36, 0x4000
	s_addc_u32 s37, s37, 0
	s_add_u32 s48, s48, 0x4000
	s_addc_u32 s49, s49, 0
	s_waitcnt vmcnt(4)
	s_barrier
	s_add_u32 m0, s51, 0x8000
	s_nop 0
	global_load_lds_dwordx4 v158, s[36:37]
	s_add_u32 m0, s51, 0xa000
	s_nop 0
	global_load_lds_dwordx4 v159, s[36:37]
	s_add_u32 m0, s51, 0x14000
	s_nop 0
	global_load_lds_dwordx4 v160, s[48:49]
	s_add_u32 m0, s51, 0x16000
	s_nop 0
	global_load_lds_dwordx4 v161, s[48:49]
	s_add_u32 s36, s36, 0x4000
	s_addc_u32 s37, s37, 0
	s_add_u32 s48, s48, 0x4000
	s_addc_u32 s49, s49, 0
	ds_read_b128 v[48:51], v144 offset:0
	ds_read_b128 v[52:55], v145 offset:0
	ds_read_b128 v[56:59], v144 offset:4096
	ds_read_b128 v[60:63], v145 offset:4096

; #define LAS __attribute__((address_space(3)))
; __device__ __forceinline__ int crow(int r, int hi) { return (r & 3) + 8 * (r >> 2) + 4 * hi; }
; #define AT_LOAD(K0, K1, V0, V1, T) do { const size_t e_ = (size_t)(128 * (T) + sr) * 64 + sc; \
;         K0 = *(const bf16x8*)(kcp + e_); V0 = *(const bf16x8*)(vcp + e_); K1 = *(const bf16x8*)(kcp + e_ + 64 * 64); V1 = *(const bf16x8*)(vcp + e_ + 64 * 64); } while (0)
; #define AT_STORE(K0, K1, V0, V1, BUF) do { *(LAS bf16x8*)(lds + AT_K + (BUF) * AT_KB + kst0) = K0; *(LAS bf16x8*)(lds + AT_K + (BUF) * AT_KB + kst1) = K1; \
;         *(LAS bf16x8*)(lds + AT_V + (BUF) * AT_VB + vst0) = V0; *(LAS bf16x8*)(lds + AT_V + (BUF) * AT_VB + vst1) = V1; } while (0)
; template <int VAR>
; __device__ __forceinline__ void attn_unit(const Args& a, int l, int b, int h, int qrow0  , bool ctxu, const bf16* Z, bf16* Y, LAS unsigned char* lds) {
;     ...
;     for (int t = 0; t < NT; t += 2) {
;         __syncthreads();
;         if (t + 2 < NT) AT_LOAD(ka0, ka1, va0, va1, t + 2);
;         attn_tile(Kb0, vb0, q0, q1, negm, m, o0, o1, lacc, t == 0, wsf, r32, hi);
;         AT_STORE(kb0, kb1, vb0_, vb1_, 1);
;         __syncthreads();
;         if (t + 3 < NT) AT_LOAD(kb0, kb1, vb0_, vb1_, t + 3);
;         attn_tile(Kb0 + AT_KB, vb0 + AT_VB, q0, q1, negm, m, o0, o1, lacc, false, wsf, r32, hi);
;         if (t + 2 < NT) AT_STORE(ka0, ka1, va0, va1, 0);
;     }
;     ...
;     float lam, omli;
;     { float s1 = 0.f, s2 = 0.f;
;       for (int i = 0; i < 32; ++i) { s1 += a.lam_q1[l * 32 + i] * a.lam_k1[l * 32 + i]; s2 += a.lam_q2[l * 32 + i] * a.lam_k2[l * 32 + i]; }
;       const float li = 0.8f - 0.6f * expf(-0.3f * (float)l); lam = expf(s1) - expf(s2) + li; omli = 1.f - li; }
;     LAS float* stg = (LAS float*)(lds + AT_ST) + wq * 2048;
;     if (comp == 1) {
; #pragma unroll
;         for (int r = 0; r < 16; ++r) { const int qr = crow(r, hi); const float il = lam * __builtin_amdgcn_rcpf(lacc[r]); stg[qr * 64 + r32] = o0[r] * il; stg[qr * 64 + 32 + r32] = o1[r] * il; }
;     }
;     __syncthreads();
;     if (comp == 0) {
; #pragma unroll
;         for (int r = 0; r < 16; ++r) { const int qr = crow(r, hi); const float il = __builtin_amdgcn_rcpf(lacc[r]); o0[r] = o0[r] * il - stg[qr * 64 + r32]; o1[r] = o1[r] * il - stg[qr * 64 + 32 + r32]; }
.Lat_ndg5:
	ds_read_b128 v[48:51], v144 offset:0
	ds_read_b128 v[52:55], v145 offset:0
	ds_read_b128 v[56:59], v144 offset:4096
	ds_read_b128 v[60:63], v145 offset:4096
	v_mfma_f32_32x32x16_bf16 v[80:95], v[162:165], v[192:195], v[80:95]
	v_mfma_f32_32x32x16_bf16 v[200:215], v[162:165], v[196:199], v[200:215]
	s_add_u32 s33, s33, 1
	s_cmp_lt_u32 s33, 22
	s_cbranch_scc1 .Lat_loop
	v_add_f32_e32 v132, v128, v129
	v_mov_b32_e32 v133, v132
	s_nop 1
	v_permlane32_swap_b32_e32 v132, v133
	v_add_f32_e32 v135, v132, v133
	v_add_f32_e32 v132, v130, v131
	v_mov_b32_e32 v133, v132
	s_nop 1
	v_permlane32_swap_b32_e32 v132, v133
	v_add_f32_e32 v130, v132, v133
	s_nop 7
	s_waitcnt lgkmcnt(0)
	ds_write_b32 v148, v135
	s_waitcnt lgkmcnt(0)
	ds_read_b128 v[32:35], v147 offset:0
	ds_read_b128 v[36:39], v147 offset:32
	ds_read_b128 v[40:43], v147 offset:64
	ds_read_b128 v[44:47], v147 offset:96
	s_waitcnt lgkmcnt(0)
	s_mov_b32 s93, 0
	s_waitcnt vmcnt(0)
	v_or_b32_e32 v132, s58, v228
	v_mov_b32_e32 v133, 0
	v_lshl_add_u64 v[132:133], v[132:133], 2, s[78:79]
	global_load_dwordx4 v[100:103], v[132:133], off offset:16
	global_load_dwordx4 v[96:99], v[132:133], off
	s_branch .LBB0_459
